# best4 + nt on attention output-gate tile LDS-DMA loads
# speedup vs baseline: 1.0049x; 1.0049x over previous
; #define DMA_K(t, slot) glds16(ksrc + (long)(t) * KVBLK * PITCH, (unsigned)__builtin_amdgcn_readfirstlane(kdst + (slot)))
;   #define CMASK(P0,P1,t) do{}while(0)
; template<int THRL> __device__ __forceinline__ void attn_unit(int b,int h,int qb,const bf16*Q,const bf16*__restrict__ K,const bf16*__restrict__ V,const unsigned short*GB,unsigned short*Y,const float*Fcum,int ts,char*shm){
;     ...
;   const bf16*Qw=Q+(rowbase+q0+wid*QBLK)*PITCH+h*D;
;   const float*Fbh=Fcum+(long)(b*NHEAD+h)*SEQ; float*Fl=(float*)(shm+LDS_F);
;   const bf16*Kh=K+(rowbase+(long)ts*KVBLK)*PITCH+h*D,*Vh=V+(rowbase+(long)ts*KVBLK)*PITCH+h*D;
;   const unsigned lds0=(unsigned)(uintptr_t)shm;
;   float*wsf=(float*)(shm+LDS_WS)+wid*64;
;   const bf16*ksrc=Kh+(long)lane*PITCH+wid*8;
;   const bf16*vsrc=Vh+(long)(16*(wid&3)+(lane>>2))*PITCH+(wid>>2)*32+(lane&3)*8;
;   const unsigned kdst=lds0+LDS_K+wid*1024, vdst=lds0+LDS_V+wid*1024;
;     ...
;   const int vb0=(int)(lds0+LDS_V)+((lane>>4)&1)*32+(lane&3)*8+(4*hi+((lane&15)>>2))*64;
;   const char*Kbase=shm+LDS_K; bf16x8 kf[8];
;   const lds_cptr shm3=(lds_cptr)shm; const lds_cptr kp0=shm3+LDS_K+hi*1024+r32*16; const lds_cptr vp0=shm3+LDS_V+((lane>>4)&1)*32+(lane&3)*8+(4*hi+((lane&15)>>2))*64;
;   const int NT=(q0+QB)/KVBLK-ts;
;   { const int np=(NT+3)>>2;
;     if(wid<np)glds16((const char*)(Fbh+64*ts)+wid*1024+lane*16,(unsigned)__builtin_amdgcn_readfirstlane(lds0+LDS_F+wid*1024));
;     if(wid+8<np)glds16((const char*)(Fbh+64*ts)+(wid+8)*1024+lane*16,(unsigned)__builtin_amdgcn_readfirstlane(lds0+LDS_F+(wid+8)*1024));
;     const unsigned short*gsrc=GB+(rowbase+q0+wid*QBLK+(lane>>3))*PITCH+h*D+(lane&7)*8;
;     #pragma unroll
;     for(int i=0;i<4;++i)glds16(gsrc+(long)i*8*PITCH,(unsigned)__builtin_amdgcn_readfirstlane(lds0+LDS_G+wid*4096+i*1024)); }
;   float nb=Fbh[q0+wid*QBLK+r32];
;   DMA_K(0,0);DMA_V(0,0);DMA_K(1,SLOTB);
;   bf16x8 qr[4];
;   #pragma unroll
;   for(int d0=0;d0<4;++d0)qr[d0]=*reinterpret_cast<const bf16x8*>(&Qw[(long)r32*PITCH+d0*16+hi*8]);
;   float mhat=0.f,l_reg=0.f;f32x16 o[2];o[0]=f32x16{};o[1]=f32x16{};
;     ...
;   const int qrel=wid*QBLK+r32;
;     ...
;   bool resc=false;
;     ...
;   f32x16 pA0,pA1,pB0,pB1;
;   int sl_prev=0,sl_cur=0,sl_next=SLOTB;
;     ...
;   DMA_K(2,2*SLOTB);
;   WAIT_BAR(3);
;   CINIT(pA0,pA1,0);
;   qkt(pA0,pA1,Kbase,qr,r32,hi);asm volatile("s_nop 15\n\ts_nop 7":"+v"(pA0),"+v"(pA1));CMASK(pA0,pA1,0);
.LBB0_213:
	s_add_u32 s16, s42, s52
	s_addc_u32 s34, s43, 0
	s_lshl_b32 s21, s31, 5
	s_ashr_i32 s36, s21, 31
	s_add_u32 s50, s16, s21
	s_addc_u32 s51, s34, s36
	s_lshl_b64 s[54:55], s[50:51], 10
	s_add_u32 s16, s89, s54
	s_addc_u32 s36, s3, s55
	s_lshl_b32 s34, s17, 7
	s_add_u32 s54, s16, s34
	s_addc_u32 s55, s36, 0
	s_ashr_i32 s41, s40, 31
	s_lshl_b64 s[60:61], s[40:41], 15
	s_add_u32 s60, s60, s44
	s_addc_u32 s61, s61, s45
	s_lshl_b64 s[60:61], s[60:61], 1
	s_add_u32 s16, s27, s60
	s_addc_u32 s36, s28, s61
	s_add_u32 s62, s16, s34
	s_addc_u32 s63, s36, 0
	s_add_u32 s16, s29, s60
	s_addc_u32 s36, s30, s61
	s_add_u32 s60, s16, s34
	v_lshlrev_b32_e32 v96, 10, v229
	s_addc_u32 s61, s36, 0
	v_lshl_add_u64 v[0:1], s[62:63], 0, v[96:97]
	s_lshl_b32 s62, s31, 3
	s_ashr_i32 s63, s62, 31
	v_lshl_add_u64 v[204:205], s[62:63], 1, v[0:1]
	s_lshl_b32 s16, s31, 4
	v_lshrrev_b32_e32 v0, 2, v229
	v_and_or_b32 v0, s16, 48, v0
	v_lshlrev_b32_e32 v96, 10, v0
	s_ashr_i32 s16, s6, 3
	v_lshl_add_u64 v[0:1], s[60:61], 0, v[96:97]
	s_and_b32 s60, s16, 0xffffffe0
	v_lshlrev_b32_e32 v2, 3, v32
	s_ashr_i32 s61, s60, 31
	v_and_b32_e32 v233, 24, v2
	v_and_b32_e32 v230, 31, v32
	v_lshl_add_u64 v[0:1], s[60:61], 1, v[0:1]
	v_lshlrev_b32_e32 v96, 1, v233
	v_lshrrev_b32_e32 v211, 3, v229
	v_lshrrev_b32_e32 v231, 5, v229
	v_lshl_add_u64 v[206:207], v[0:1], 0, v[96:97]
	v_lshlrev_b32_e32 v0, 4, v230
	v_or_b32_e32 v202, s50, v211
	v_mov_b32_e32 v203, s51
	v_lshl_or_b32 v239, v231, 10, v0
	v_lshlrev_b64 v[0:1], 10, v[202:203]
	v_lshl_add_u64 v[0:1], s[10:11], 0, v[0:1]
	v_and_b32_e32 v2, 56, v2
	s_lshl_b32 s68, s31, 12
	v_lshl_add_u64 v[0:1], v[0:1], 0, s[34:35]
	v_lshlrev_b32_e32 v96, 1, v2
	s_add_i32 s31, s68, 0x18800
	v_lshl_add_u64 v[0:1], v[0:1], 0, v[96:97]
	s_mov_b32 s34, m0
	s_mov_b32 m0, s31
	s_nop 0
	global_load_lds_dwordx4 v[0:1], off nt
	s_mov_b32 m0, s34
	s_mov_b64 s[60:61], 0x2000
	s_add_i32 s31, s68, 0x18c00
	v_lshl_add_u64 v[2:3], v[0:1], 0, s[60:61]
	s_mov_b32 s34, m0
	s_mov_b32 m0, s31
	s_nop 0
	global_load_lds_dwordx4 v[2:3], off nt
	s_mov_b32 m0, s34
	s_add_i32 s31, s68, 0x19000
	v_lshl_add_u64 v[2:3], v[0:1], 0, s[96:97]
	s_mov_b32 s34, m0
	s_mov_b32 m0, s31
	s_nop 0
	global_load_lds_dwordx4 v[2:3], off nt
	s_mov_b32 m0, s34
	s_mov_b64 s[60:61], 0x6000
	s_add_i32 s31, s68, 0x19400
	v_lshl_add_u64 v[0:1], v[0:1], 0, s[60:61]
	s_mov_b32 s34, m0
	s_mov_b32 m0, s31
	s_nop 0
	global_load_lds_dwordx4 v[0:1], off nt
	s_mov_b32 m0, s34
	s_add_i32 s31, s21, s52
	v_or_b32_e32 v0, s31, v230
	v_ashrrev_i32_e32 v1, 31, v0
	v_lshl_add_u64 v[0:1], v[0:1], 2, s[38:39]
	global_load_dword v33, v[0:1], off
	s_mov_b32 s31, m0
	s_mov_b32 m0, s0
	s_nop 0
	global_load_lds_dwordx4 v[204:205], off
	s_mov_b32 m0, s31
	s_add_i32 s16, s0, 0x6000
	s_mov_b32 s31, m0
	s_mov_b32 m0, s16
	s_nop 0
	global_load_lds_dwordx4 v[206:207], off
	s_mov_b32 m0, s31
	v_lshl_add_u64 v[0:1], v[204:205], 0, s[18:19]
	v_lshlrev_b32_e32 v28, 4, v231
	s_add_i32 s31, s0, 0x2000
	s_mov_b32 s34, m0
	s_mov_b32 m0, s31
	s_nop 0
	global_load_lds_dwordx4 v[0:1], off
	s_mov_b32 m0, s34
	v_lshl_or_b32 v0, v230, 10, v28
	global_load_dwordx4 v[110:113], v0, s[54:55]
	global_load_dwordx4 v[106:109], v0, s[54:55] offset:32
	global_load_dwordx4 v[102:105], v0, s[54:55] offset:64
	global_load_dwordx4 v[98:101], v0, s[54:55] offset:96
	v_lshl_add_u64 v[0:1], v[204:205], 0, s[56:57]
	s_add_i32 s31, s0, 0x4000
	s_mov_b32 s34, m0
	s_mov_b32 m0, s31
	s_nop 0
	global_load_lds_dwordx4 v[0:1], off
	s_mov_b32 m0, s34
	s_waitcnt vmcnt(3) lgkmcnt(0)
	s_barrier
	v_or_b32_e32 v0, 0x14800, v28
	s_waitcnt vmcnt(5)
	v_or_b32_e32 v4, 0x14880, v28
	ds_read_b128 v[0:3], v0
	ds_read_b128 v[16:19], v4
	v_or_b32_e32 v4, 0x14820, v28
	v_or_b32_e32 v8, 0x148a0, v28
	ds_read_b128 v[4:7], v4
	ds_read_b128 v[20:23], v8
	v_or_b32_e32 v8, 0x14840, v28
	v_or_b32_e32 v12, 0x148c0, v28
	ds_read_b128 v[8:11], v8
	ds_read_b128 v[24:27], v12
	v_or_b32_e32 v12, 0x14860, v28
	v_or_b32_e32 v28, 0x148e0, v28
	ds_read_b128 v[12:15], v12
	ds_read_b128 v[28:31], v28
	ds_read_b128 v[34:37], v239
	ds_read_b128 v[38:41], v239 offset:512
	v_lshlrev_b32_e32 v232, 2, v231
	v_or_b32_e32 v237, s21, v230
	s_cmp_gt_i32 s12, 4
	s_waitcnt vmcnt(4) lgkmcnt(3)
	v_sub_f32_e32 v15, v33, v15
	v_sub_f32_e32 v14, v33, v14
	v_sub_f32_e32 v13, v33, v13
	v_sub_f32_e32 v12, v33, v12
	v_sub_f32_e32 v11, v33, v11
	v_sub_f32_e32 v10, v33, v10
	v_sub_f32_e32 v9, v33, v9
	v_sub_f32_e32 v8, v33, v8
	v_sub_f32_e32 v7, v33, v7
	v_sub_f32_e32 v6, v33, v6
	v_sub_f32_e32 v5, v33, v5
	v_sub_f32_e32 v4, v33, v4
	v_sub_f32_e32 v3, v33, v3
	v_sub_f32_e32 v2, v33, v2
	v_sub_f32_e32 v1, v33, v1
	v_sub_f32_e32 v0, v33, v0
	s_waitcnt lgkmcnt(2)
	v_sub_f32_e32 v31, v33, v31
	v_sub_f32_e32 v30, v33, v30
	v_sub_f32_e32 v29, v33, v29
	v_sub_f32_e32 v28, v33, v28
	v_sub_f32_e32 v27, v33, v27
	v_sub_f32_e32 v26, v33, v26
	v_sub_f32_e32 v25, v33, v25
	v_sub_f32_e32 v24, v33, v24
	v_sub_f32_e32 v23, v33, v23
	v_sub_f32_e32 v22, v33, v22
	v_sub_f32_e32 v21, v33, v21
	v_sub_f32_e32 v20, v33, v20
	v_sub_f32_e32 v19, v33, v19
	v_sub_f32_e32 v18, v33, v18
	v_sub_f32_e32 v17, v33, v17
	v_sub_f32_e32 v16, v33, v16
	s_waitcnt vmcnt(3) lgkmcnt(1)
	v_mfma_f32_32x32x16_bf16 v[0:15], v[34:37], v[110:113], v[0:15]
	s_waitcnt lgkmcnt(0)
	v_mfma_f32_32x32x16_bf16 v[16:31], v[38:41], v[110:113], v[16:31]
	ds_read_b128 v[34:37], v239 offset:2048
	ds_read_b128 v[38:41], v239 offset:2560
	s_waitcnt vmcnt(2) lgkmcnt(1)
	v_mfma_f32_32x32x16_bf16 v[0:15], v[34:37], v[106:109], v[0:15]
	s_waitcnt lgkmcnt(0)
	v_mfma_f32_32x32x16_bf16 v[16:31], v[38:41], v[106:109], v[16:31]
	ds_read_b128 v[34:37], v239 offset:4096
	ds_read_b128 v[38:41], v239 offset:4608
	s_waitcnt vmcnt(1) lgkmcnt(1)
	v_mfma_f32_32x32x16_bf16 v[0:15], v[34:37], v[102:105], v[0:15]
	s_waitcnt lgkmcnt(0)
	v_mfma_f32_32x32x16_bf16 v[16:31], v[38:41], v[102:105], v[16:31]
	ds_read_b128 v[34:37], v239 offset:6144
	ds_read_b128 v[38:41], v239 offset:6656
	s_waitcnt vmcnt(0) lgkmcnt(1)
	v_mfma_f32_32x32x16_bf16 v[0:15], v[34:37], v[98:101], v[0:15]
	s_waitcnt lgkmcnt(0)
	v_mfma_f32_32x32x16_bf16 v[16:31], v[38:41], v[98:101], v[16:31]
	s_nop 15
	s_nop 7
	s_cbranch_scc1 .LBB0_215
; __device__ __forceinline__ void cmask(f32x16&p0,f32x16&p1,int jb,int qrel,int hi){
;   const float NEG=-INFINITY; int kb=64*jb+4*hi;
;   #pragma unroll
;   for(int r=0;r<16;++r){int kv=kb+(r&3)+8*(r>>2); if(kv>qrel)p0[r]=NEG; if(kv+32>qrel)p1[r]=NEG;}
; }
	s_lshl_b32 s21, s12, 6
	v_subrev_u32_e32 v34, s21, v232
	v_add_u32_e32 v36, 0x120, v34
	v_add_u32_e32 v35, 0x100, v34
	v_cmp_le_i32_e32 vcc, v36, v237
	s_nop 5
	v_cndmask_b32_e32 v16, v227, v16, vcc
	v_cmp_lt_i32_e32 vcc, v35, v237
	s_nop 1
	v_cndmask_b32_e32 v1, v227, v1, vcc
	v_cmp_le_i32_e32 vcc, v35, v237
	v_add_u32_e32 v35, 0x121, v34
	s_nop 0
	v_cndmask_b32_e32 v0, v227, v0, vcc
	v_cmp_le_i32_e32 vcc, v35, v237
	v_add_u32_e32 v35, 0x102, v34
	s_nop 0
	v_cndmask_b32_e32 v17, v227, v17, vcc
	v_cmp_le_i32_e32 vcc, v35, v237
	v_add_u32_e32 v35, 0x122, v34
	s_nop 0
	v_cndmask_b32_e32 v2, v227, v2, vcc
	v_cmp_le_i32_e32 vcc, v35, v237
	v_add_u32_e32 v35, 0x103, v34
	s_nop 0
	v_cndmask_b32_e32 v18, v227, v18, vcc
	v_cmp_le_i32_e32 vcc, v35, v237
	v_add_u32_e32 v35, 0x123, v34
	s_nop 0
	v_cndmask_b32_e32 v3, v227, v3, vcc
	v_cmp_le_i32_e32 vcc, v35, v237
	v_add_u32_e32 v35, 0x108, v34
	s_nop 0
	v_cndmask_b32_e32 v19, v227, v19, vcc
	v_cmp_le_i32_e32 vcc, v35, v237
	v_add_u32_e32 v35, 0x128, v34
	s_nop 0
	v_cndmask_b32_e32 v4, v227, v4, vcc
	v_cmp_le_i32_e32 vcc, v35, v237
	v_add_u32_e32 v35, 0x109, v34
	s_nop 0
	v_cndmask_b32_e32 v20, v227, v20, vcc
	v_cmp_le_i32_e32 vcc, v35, v237
	v_add_u32_e32 v35, 0x129, v34
	s_nop 0
	v_cndmask_b32_e32 v5, v227, v5, vcc
	v_cmp_le_i32_e32 vcc, v35, v237
	v_add_u32_e32 v35, 0x10a, v34
	s_nop 0
	v_cndmask_b32_e32 v21, v227, v21, vcc
	v_cmp_le_i32_e32 vcc, v35, v237
	v_add_u32_e32 v35, 0x12a, v34
	s_nop 0
	v_cndmask_b32_e32 v6, v227, v6, vcc
	v_cmp_le_i32_e32 vcc, v35, v237
	v_add_u32_e32 v35, 0x10b, v34
	s_nop 0
	v_cndmask_b32_e32 v22, v227, v22, vcc
	v_cmp_le_i32_e32 vcc, v35, v237
	v_add_u32_e32 v35, 0x12b, v34
	s_nop 0
	v_cndmask_b32_e32 v7, v227, v7, vcc
	v_cmp_le_i32_e32 vcc, v35, v237
	v_add_u32_e32 v35, 0x110, v34
	s_nop 0
	v_cndmask_b32_e32 v23, v227, v23, vcc
	v_cmp_le_i32_e32 vcc, v35, v237
	v_add_u32_e32 v35, 0x130, v34
	s_nop 0
	v_cndmask_b32_e32 v8, v227, v8, vcc
	v_cmp_le_i32_e32 vcc, v35, v237
	v_add_u32_e32 v35, 0x111, v34
	s_nop 0
	v_cndmask_b32_e32 v24, v227, v24, vcc
	v_cmp_le_i32_e32 vcc, v35, v237
	v_add_u32_e32 v35, 0x131, v34
	s_nop 0
	v_cndmask_b32_e32 v9, v227, v9, vcc
	v_cmp_le_i32_e32 vcc, v35, v237
	v_add_u32_e32 v35, 0x112, v34
	s_nop 0
	v_cndmask_b32_e32 v25, v227, v25, vcc
	v_cmp_le_i32_e32 vcc, v35, v237
	v_add_u32_e32 v35, 0x132, v34
	s_nop 0
	v_cndmask_b32_e32 v10, v227, v10, vcc
	v_cmp_le_i32_e32 vcc, v35, v237
	v_add_u32_e32 v35, 0x113, v34
	s_nop 0
	v_cndmask_b32_e32 v26, v227, v26, vcc
	v_cmp_le_i32_e32 vcc, v35, v237
	v_add_u32_e32 v35, 0x133, v34
	s_nop 0
	v_cndmask_b32_e32 v11, v227, v11, vcc
	v_cmp_le_i32_e32 vcc, v35, v237
	v_add_u32_e32 v35, 0x118, v34
	s_nop 0
	v_cndmask_b32_e32 v27, v227, v27, vcc
	v_cmp_le_i32_e32 vcc, v35, v237
	v_add_u32_e32 v35, 0x138, v34
	s_nop 0
	v_cndmask_b32_e32 v12, v227, v12, vcc
	v_cmp_le_i32_e32 vcc, v35, v237
	v_add_u32_e32 v35, 0x119, v34
	s_nop 0
	v_cndmask_b32_e32 v28, v227, v28, vcc
	v_cmp_le_i32_e32 vcc, v35, v237
	v_add_u32_e32 v35, 0x139, v34
	s_nop 0
	v_cndmask_b32_e32 v13, v227, v13, vcc
	v_cmp_le_i32_e32 vcc, v35, v237
	v_add_u32_e32 v35, 0x11a, v34
	s_nop 0
	v_cndmask_b32_e32 v29, v227, v29, vcc
	v_cmp_le_i32_e32 vcc, v35, v237
	v_add_u32_e32 v35, 0x13a, v34
	s_nop 0
	v_cndmask_b32_e32 v14, v227, v14, vcc
	v_cmp_le_i32_e32 vcc, v35, v237
	v_add_u32_e32 v35, 0x11b, v34
	v_add_u32_e32 v34, 0x13b, v34
	v_cndmask_b32_e32 v30, v227, v30, vcc
	v_cmp_le_i32_e32 vcc, v35, v237
	s_nop 1
	v_cndmask_b32_e32 v15, v227, v15, vcc
	v_cmp_le_i32_e32 vcc, v34, v237
	s_nop 1
	v_cndmask_b32_e32 v31, v227, v31, vcc
